# M3 ssmy units too: y_intra pieces loaded into free registers so their unpack (and the early vmcnt(0) it needed) moves behind the load barrier; one load round trip per M3 unit
# speedup vs baseline: 1.0076x; 1.0015x over previous
.LBB0_923:
	s_ashr_i32 s2, s23, 31
	s_lshr_b32 s2, s2, 24
	s_add_i32 s2, s23, s2
	s_ashr_i32 s12, s2, 8
	s_and_b32 s2, s2, 0xffffff00
	s_sub_i32 s2, s23, s2
	s_ashr_i32 s10, s2, 1
	v_mov_b32_e32 v14, v30
	s_add_i32 s10, s10, 1
	s_mul_i32 s2, s12, 0x81
	v_readfirstlane_b32 s13, v14
	s_bfe_u32 s27, s13, 0x10007
	s_and_b32 s24, s14, 2
	s_add_i32 s2, s10, s2
	s_lshl_b32 s21, s2, 2
	s_or_b32 s2, s27, s24
	s_or_b32 s2, s2, s21
	s_ashr_i32 s11, s13, 6
	s_ashr_i32 s3, s2, 31
	s_lshl_b32 s20, s11, 3
	s_mul_i32 s25, s2, 0xa000
	s_mul_hi_i32 s26, s2, 0xa000
	s_lshl_b64 s[2:3], s[2:3], 14
	s_cmp_lt_i32 s11, 4
	v_lshl_add_u32 v0, s27, 14, v31
	s_cselect_b64 vcc, -1, 0
	s_lshl_b32 s27, s11, 13
	s_and_b32 s27, s27, 0x2000
	s_and_b64 s[28:29], vcc, exec
	s_cselect_b32 s29, 0x1ab00000, s25
	s_cselect_b32 s28, 0, s26
	s_cselect_b32 s30, s3, 0
	s_cselect_b32 s31, s2, 0x18204000
	s_add_u32 s29, s4, s29
	v_add_u32_e32 v1, 0x8000, v0
	s_addc_u32 s28, s5, s28
	v_cndmask_b32_e32 v3, v1, v0, vcc
	s_add_u32 s29, s29, s31
	s_addc_u32 s30, s28, s30
	v_add_u32_e32 v3, s27, v3
	s_add_u32 s28, s29, s27
	v_readfirstlane_b32 s27, v3
	s_addc_u32 s29, s30, 0
	s_mov_b32 m0, s27
	s_or_b32 s27, s20, 1
	v_and_b32_e32 v26, 63, v14
	s_cmp_lt_i32 s27, 32
	v_lshlrev_b32_e32 v2, 4, v26
	s_cselect_b64 vcc, -1, 0
	global_load_lds_dwordx4 v2, s[28:29]
	s_and_b64 s[28:29], vcc, exec
	s_cselect_b32 s29, 0x1ab00000, s25
	s_cselect_b32 s28, 0, s26
	s_cselect_b32 s30, s3, 0
	s_cselect_b32 s31, s2, 0x18204000
	s_add_u32 s29, s4, s29
	s_addc_u32 s28, s5, s28
	s_add_u32 s29, s29, s31
	s_addc_u32 s30, s28, s30
	s_lshl_b32 s27, s27, 10
	v_cndmask_b32_e32 v3, v1, v0, vcc
	s_and_b32 s27, s27, 0x2400
	v_add_u32_e32 v3, s27, v3
	s_add_u32 s28, s29, s27
	v_readfirstlane_b32 s27, v3
	s_addc_u32 s29, s30, 0
	s_mov_b32 m0, s27
	s_or_b32 s27, s20, 2
	s_cmp_lt_i32 s27, 32
	s_cselect_b64 vcc, -1, 0
	global_load_lds_dwordx4 v2, s[28:29]
	s_and_b64 s[28:29], vcc, exec
	s_cselect_b32 s29, 0x1ab00000, s25
	s_cselect_b32 s28, 0, s26
	s_cselect_b32 s30, s3, 0
	s_cselect_b32 s31, s2, 0x18204000
	s_add_u32 s29, s4, s29
	s_addc_u32 s28, s5, s28
	s_add_u32 s29, s29, s31
	s_addc_u32 s30, s28, s30
	s_lshl_b32 s27, s27, 10
	v_cndmask_b32_e32 v3, v1, v0, vcc
	s_and_b32 s27, s27, 0x2800
	v_add_u32_e32 v3, s27, v3
	s_add_u32 s28, s29, s27
	v_readfirstlane_b32 s27, v3
	s_addc_u32 s29, s30, 0
	s_mov_b32 m0, s27
	s_or_b32 s27, s20, 3
	s_cmp_lt_i32 s27, 32
	s_cselect_b64 vcc, -1, 0
	global_load_lds_dwordx4 v2, s[28:29]
	s_and_b64 s[28:29], vcc, exec
	s_cselect_b32 s29, 0x1ab00000, s25
	s_cselect_b32 s28, 0, s26
	s_cselect_b32 s30, s3, 0
	s_cselect_b32 s31, s2, 0x18204000
	s_add_u32 s29, s4, s29
	s_addc_u32 s28, s5, s28
	s_add_u32 s29, s29, s31
	s_addc_u32 s30, s28, s30
	s_lshl_b32 s27, s27, 10
	v_cndmask_b32_e32 v3, v1, v0, vcc
	s_and_b32 s27, s27, 0x2c00
	v_add_u32_e32 v3, s27, v3
	s_add_u32 s28, s29, s27
	v_readfirstlane_b32 s27, v3
	s_addc_u32 s29, s30, 0
	s_mov_b32 m0, s27
	s_or_b32 s27, s20, 4
	s_cmp_lt_i32 s27, 32
	s_cselect_b64 vcc, -1, 0
	global_load_lds_dwordx4 v2, s[28:29]
	s_and_b64 s[28:29], vcc, exec
	s_cselect_b32 s29, 0x1ab00000, s25
	s_cselect_b32 s28, 0, s26
	s_cselect_b32 s30, s3, 0
	s_cselect_b32 s31, s2, 0x18204000
	s_add_u32 s29, s4, s29
	s_addc_u32 s28, s5, s28
	s_add_u32 s29, s29, s31
	s_addc_u32 s30, s28, s30
	s_lshl_b32 s27, s27, 10
	v_cndmask_b32_e32 v3, v1, v0, vcc
	s_and_b32 s27, s27, 0x3000
	v_add_u32_e32 v3, s27, v3
	s_add_u32 s28, s29, s27
	v_readfirstlane_b32 s27, v3
	s_addc_u32 s29, s30, 0
	s_mov_b32 m0, s27
	s_or_b32 s27, s20, 5
	s_cmp_lt_i32 s27, 32
	s_cselect_b64 vcc, -1, 0
	global_load_lds_dwordx4 v2, s[28:29]
	s_and_b64 s[28:29], vcc, exec
	s_cselect_b32 s29, 0x1ab00000, s25
	s_cselect_b32 s28, 0, s26
	s_cselect_b32 s30, s3, 0
	s_cselect_b32 s31, s2, 0x18204000
	s_add_u32 s29, s4, s29
	s_addc_u32 s28, s5, s28
	s_add_u32 s29, s29, s31
	s_addc_u32 s30, s28, s30
	s_lshl_b32 s27, s27, 10
	v_cndmask_b32_e32 v3, v1, v0, vcc
	s_and_b32 s27, s27, 0x3400
	v_add_u32_e32 v3, s27, v3
	s_add_u32 s28, s29, s27
	v_readfirstlane_b32 s27, v3
	s_addc_u32 s29, s30, 0
	s_mov_b32 m0, s27
	s_or_b32 s27, s20, 6
	s_cmp_lt_i32 s27, 32
	s_cselect_b64 vcc, -1, 0
	global_load_lds_dwordx4 v2, s[28:29]
	s_and_b64 s[28:29], vcc, exec
	s_cselect_b32 s29, 0x1ab00000, s25
	s_cselect_b32 s28, 0, s26
	s_cselect_b32 s30, s3, 0
	s_cselect_b32 s31, s2, 0x18204000
	s_add_u32 s29, s4, s29
	s_addc_u32 s28, s5, s28
	s_add_u32 s29, s29, s31
	s_addc_u32 s30, s28, s30
	s_lshl_b32 s27, s27, 10
	s_and_b32 s27, s27, 0x3800
	v_cndmask_b32_e32 v3, v1, v0, vcc
	s_add_u32 s28, s29, s27
	s_addc_u32 s29, s30, 0
	v_add_u32_e32 v3, s27, v3
	s_or_b32 s20, s20, 7
	v_readfirstlane_b32 s27, v3
	s_cmp_lt_i32 s20, 32
	s_mov_b32 m0, s27
	s_cselect_b64 vcc, -1, 0
	global_load_lds_dwordx4 v2, s[28:29]
	s_and_b64 s[28:29], vcc, exec
	s_cselect_b32 s25, 0x1ab00000, s25
	s_cselect_b32 s26, 0, s26
	s_cselect_b32 s3, s3, 0
	s_cselect_b32 s2, s2, 0x18204000
	s_add_u32 s25, s4, s25
	s_addc_u32 s26, s5, s26
	s_add_u32 s2, s25, s2
	s_addc_u32 s3, s26, s3
	s_lshl_b32 s20, s20, 10
	v_cndmask_b32_e32 v0, v1, v0, vcc
	s_and_b32 s20, s20, 0x3c00
	v_add_u32_e32 v0, s20, v0
	s_add_u32 s2, s2, s20
	v_readfirstlane_b32 s20, v0
	s_addc_u32 s3, s3, 0
	s_mov_b32 m0, s20
	s_ashr_i32 s20, s13, 8
	v_and_b32_e32 v15, 15, v14
	global_load_lds_dwordx4 v2, s[2:3]
	s_add_i32 s13, s20, s24
	s_lshl_b32 s2, s11, 4
	v_and_or_b32 v27, s2, 48, v15
	s_add_i32 s2, s21, s13
	s_mul_hi_i32 s3, s2, 0xa000
	s_mul_i32 s2, s2, 0xa000
	s_add_u32 s2, s4, s2
	s_addc_u32 s3, s5, s3
	v_lshlrev_b32_e32 v10, 4, v14
	s_add_u32 s2, s2, 0x18208000
	v_and_b32_e32 v16, 48, v14
	v_lshlrev_b32_e32 v0, 7, v27
	v_and_b32_e32 v17, 0x70, v10
	s_addc_u32 s3, s3, 0
	v_bitop3_b32 v12, v0, v17, v16 bitop3:0xf6
	v_or_b32_e32 v18, 64, v16
	v_bitop3_b32 v13, v0, v17, v18 bitop3:0xf6
	global_load_dwordx4 v[116:119], v12, s[2:3]
	global_load_dwordx4 v[120:123], v13, s[2:3]
	v_lshl_or_b32 v19, s10, 6, v27
	v_cmp_lt_i32_e32 vcc, 47, v19
	v_mov_b64_e32 v[12:13], 0
	s_and_saveexec_b64 s[10:11], vcc
	s_cbranch_execz .LBB0_929
	v_subrev_u32_e32 v13, 48, v19
	v_cmp_lt_u32_e64 s[2:3], 15, v13
	s_and_saveexec_b64 s[24:25], s[2:3]
	s_xor_b64 s[2:3], exec, s[24:25]
	s_lshl_b32 s21, s12, 13
	s_sub_i32 s21, s21, 64
	v_add_u32_e32 v12, s21, v19
	s_andn2_saveexec_b64 s[2:3], s[2:3]
	s_lshl_b32 s12, s12, 4
	s_addk_i32 s12, 0x4400
	v_or_b32_e32 v12, s12, v13
	s_or_b64 exec, exec, s[2:3]
	v_ashrrev_i32_e32 v13, 31, v12
.LBB0_929:
	s_or_b64 exec, exec, s[10:11]
	s_nop 0
	s_lshl_b32 s10, s13, 6
	v_lshrrev_b32_e32 v2, 1, v14
	v_mad_i64_i32 v[0:1], s[2:3], v12, s17, v[8:9]
	s_ashr_i32 s11, s10, 31
	v_and_b32_e32 v28, 24, v2
	v_bitop3_b32 v20, v10, v16, s16 bitop3:0x6c
	v_bitop3_b32 v19, v10, v18, s16 bitop3:0x6c
	v_lshl_add_u64 v[0:1], s[10:11], 1, v[0:1]
	v_lshlrev_b32_e32 v10, 1, v28
	v_lshl_add_u64 v[0:1], v[0:1], 0, v[10:11]
	v_add_co_u32_e64 v48, s[2:3], s18, v0
	s_nop 0
	v_addc_co_u32_e64 v49, s[2:3], 0, v1, s[2:3]
	v_lshl_add_u64 v[42:43], v[0:1], 0, s[6:7]
	global_load_dwordx4 v[44:47], v[48:49], off offset:1536
	global_load_dwordx4 v[0:3], v[42:43], off offset:64
	v_lshl_add_u32 v4, s20, 14, v31
	v_lshlrev_b32_e32 v15, 1, v15
	v_and_b32_e32 v14, 3, v14
	v_lshl_add_u32 v10, v27, 8, v4
	v_and_or_b32 v15, v15, 24, v14
	s_waitcnt vmcnt(0) lgkmcnt(0)
	s_barrier
	v_lshlrev_b32_e32 v36, 16, v118
	v_and_b32_e32 v37, 0xffff0000, v118
	v_lshlrev_b32_e32 v32, 16, v116
	v_and_b32_e32 v33, 0xffff0000, v116
	v_lshlrev_b32_e32 v34, 16, v117
	v_and_b32_e32 v35, 0xffff0000, v117
	v_lshlrev_b32_e32 v38, 16, v119
	v_and_b32_e32 v39, 0xffff0000, v119
	v_lshlrev_b32_e32 v40, 16, v120
	v_and_b32_e32 v41, 0xffff0000, v120
	v_lshlrev_b32_e32 v29, 4, v14
	v_add_u32_e32 v14, v10, v20
	v_lshl_add_u32 v64, v15, 8, v4
	v_xad_u32 v20, v29, v16, v64
	ds_read_b128 v[48:51], v14 offset:32768
	ds_read_b128 v[52:55], v20
	v_lshlrev_b32_e32 v42, 16, v121
	v_and_b32_e32 v43, 0xffff0000, v121
	v_or_b32_e32 v5, 4, v15
	v_lshlrev_b32_e32 v14, 4, v5
	v_and_b32_e32 v65, 0x70, v14
	v_lshl_add_u32 v66, v5, 8, v4
	v_xad_u32 v5, v65, v16, v66
	ds_read_b128 v[56:59], v5
	s_waitcnt lgkmcnt(0)
	v_mfma_f32_16x16x32_bf16 v[32:35], v[52:55], v[48:51], v[32:35]
	ds_read_b128 v[52:55], v20 offset:8192
	v_or_b32_e32 v5, 36, v15
	v_lshlrev_b32_e32 v14, 4, v5
	v_and_b32_e32 v67, 0x70, v14
	v_lshl_add_u32 v68, v5, 8, v4
	v_xad_u32 v4, v67, v16, v68
	ds_read_b128 v[60:63], v4
	v_add_u32_e32 v14, v10, v19
	v_and_b32_e32 v5, 0xffff0000, v122
	s_waitcnt lgkmcnt(1)
	v_mfma_f32_16x16x32_bf16 v[40:43], v[52:55], v[48:51], v[40:43]
	ds_read_b128 v[52:55], v14 offset:32768
	v_lshlrev_b32_e32 v4, 16, v122
	v_lshlrev_b32_e32 v6, 16, v123
	v_and_b32_e32 v7, 0xffff0000, v123
	v_xad_u32 v14, v29, v18, v64
	v_mfma_f32_16x16x32_bf16 v[36:39], v[56:59], v[48:51], v[36:39]
	v_cmp_gt_u32_e64 s[2:3], 16, v26
	s_waitcnt lgkmcnt(1)
	v_mfma_f32_16x16x32_bf16 v[4:7], v[60:63], v[48:51], v[4:7]
	ds_read_b128 v[48:51], v14
	ds_read_b128 v[56:59], v14 offset:8192
	v_xad_u32 v14, v65, v18, v66
	s_waitcnt lgkmcnt(1)
	v_mfma_f32_16x16x32_bf16 v[32:35], v[48:51], v[52:55], v[32:35]
	ds_read_b128 v[48:51], v14
	v_xad_u32 v14, v67, v18, v68
	ds_read_b128 v[18:21], v14
	v_or_b32_e32 v14, 0x80, v16
	v_xad_u32 v15, v29, v14, v64
	s_waitcnt lgkmcnt(1)
	v_mfma_f32_16x16x32_bf16 v[36:39], v[48:51], v[52:55], v[36:39]
	ds_read_b128 v[48:51], v15
	s_waitcnt lgkmcnt(1)
	v_mfma_f32_16x16x32_bf16 v[4:7], v[18:21], v[52:55], v[4:7]
	v_xad_u32 v18, v17, v14, v10
	ds_read_b128 v[18:21], v18 offset:32768
	s_waitcnt lgkmcnt(0)
	v_mfma_f32_16x16x32_bf16 v[32:35], v[48:51], v[18:21], v[32:35]
	v_xad_u32 v48, v65, v14, v66
	v_xad_u32 v14, v67, v14, v68
	v_mfma_f32_16x16x32_bf16 v[40:43], v[56:59], v[52:55], v[40:43]
	ds_read_b128 v[48:51], v48
	ds_read_b128 v[52:55], v15 offset:8192
	s_waitcnt vmcnt(1)
	v_lshlrev_b32_e32 v56, 16, v44
	s_waitcnt lgkmcnt(1)
	v_mfma_f32_16x16x32_bf16 v[36:39], v[48:51], v[18:21], v[36:39]
	ds_read_b128 v[48:51], v14
	v_and_b32_e32 v57, 0xffff0000, v44
	s_waitcnt lgkmcnt(1)
	v_mfma_f32_16x16x32_bf16 v[40:43], v[52:55], v[18:21], v[40:43]
	v_or_b32_e32 v52, 0xc0, v16
	v_xad_u32 v10, v17, v52, v10
	ds_read_b128 v[14:17], v10 offset:32768
	v_xad_u32 v10, v29, v52, v64
	s_waitcnt lgkmcnt(1)
	v_mfma_f32_16x16x32_bf16 v[4:7], v[48:51], v[18:21], v[4:7]
	ds_read_b128 v[18:21], v10
	ds_read_b128 v[48:51], v10 offset:8192
	v_xad_u32 v10, v65, v52, v66
	v_mul_f32_e32 v29, 0xbfb8aa3b, v57
	s_waitcnt lgkmcnt(1)
	v_mfma_f32_16x16x32_bf16 v[18:21], v[18:21], v[14:17], v[32:35]
	v_exp_f32_e32 v29, v29
	s_nop 1
	ds_read_b128 v[32:35], v10
	v_xad_u32 v10, v67, v52, v68
	ds_read_b128 v[52:55], v10
	v_mul_f32_e32 v10, 0xbfb8aa3b, v56
	v_exp_f32_e32 v10, v10
	s_waitcnt lgkmcnt(1)
	v_mfma_f32_16x16x32_bf16 v[32:35], v[32:35], v[14:17], v[36:39]
	v_add_f32_e32 v10, 1.0, v10
	v_rcp_f32_e32 v44, v10
	v_add_f32_e32 v10, 1.0, v29
	v_mfma_f32_16x16x32_bf16 v[36:39], v[48:51], v[14:17], v[40:43]
	v_lshlrev_b32_e32 v48, 16, v45
	v_and_b32_e32 v49, 0xffff0000, v45
	v_mul_f32_e32 v29, 0xbfb8aa3b, v48
	v_exp_f32_e32 v29, v29
	v_mul_f32_e32 v40, 0xbfb8aa3b, v49
	v_exp_f32_e32 v40, v40
	v_rcp_f32_e32 v45, v10
	v_add_f32_e32 v10, 1.0, v29
	v_rcp_f32_e32 v50, v10
	v_add_f32_e32 v10, 1.0, v40
	s_waitcnt lgkmcnt(0)
	v_mfma_f32_16x16x32_bf16 v[40:43], v[52:55], v[14:17], v[4:7]
	v_lshlrev_b32_e32 v14, 16, v46
	v_rcp_f32_e32 v51, v10
	v_and_b32_e32 v15, 0xffff0000, v46
	v_mul_f32_e32 v10, 0xbfb8aa3b, v14
	v_exp_f32_e32 v10, v10
	v_mul_f32_e32 v16, 0xbfb8aa3b, v15
	v_exp_f32_e32 v17, v16
	v_pk_mul_f32 v[4:5], v[44:45], v[56:57]
	v_add_f32_e32 v10, 1.0, v10
	v_pk_mul_f32 v[4:5], v[4:5], v[18:19]
	v_lshlrev_b32_e32 v18, 16, v47
	v_pk_mul_f32 v[6:7], v[50:51], v[48:49]
	v_rcp_f32_e32 v16, v10
	v_add_f32_e32 v10, 1.0, v17
	v_and_b32_e32 v19, 0xffff0000, v47
	v_mul_f32_e32 v17, 0xbfb8aa3b, v18
	v_pk_mul_f32 v[6:7], v[6:7], v[20:21]
	v_exp_f32_e32 v20, v17
	v_mul_f32_e32 v17, 0xbfb8aa3b, v19
	v_exp_f32_e32 v21, v17
	v_rcp_f32_e32 v17, v10
	v_add_f32_e32 v10, 1.0, v20
	v_rcp_f32_e32 v20, v10
	v_add_f32_e32 v10, 1.0, v21
	v_rcp_f32_e32 v21, v10
	v_pk_mul_f32 v[14:15], v[16:17], v[14:15]
	v_pk_mul_f32 v[44:45], v[4:5], v[4:5]
	v_pk_mul_f32 v[14:15], v[14:15], v[32:33]
	v_pk_mul_f32 v[16:17], v[20:21], v[18:19]
	s_waitcnt vmcnt(0)
	v_and_b32_e32 v19, 0xffff0000, v0
	v_mul_f32_e32 v10, 0xbfb8aa3b, v19
	v_lshlrev_b32_e32 v20, 16, v1
	v_lshlrev_b32_e32 v18, 16, v0
	v_exp_f32_e32 v10, v10
	v_and_b32_e32 v21, 0xffff0000, v1
	v_mul_f32_e32 v1, 0xbfb8aa3b, v20
	v_mul_f32_e32 v0, 0xbfb8aa3b, v18
	v_exp_f32_e32 v29, v1
	v_mul_f32_e32 v1, 0xbfb8aa3b, v21
	v_pk_mul_f32 v[16:17], v[16:17], v[34:35]
	v_exp_f32_e32 v0, v0
	v_exp_f32_e32 v35, v1
	v_add_f32_e32 v10, 1.0, v10
	v_rcp_f32_e32 v1, v10
	v_add_f32_e32 v10, 1.0, v29
	v_add_f32_e32 v0, 1.0, v0
	v_rcp_f32_e32 v34, v10
	v_add_f32_e32 v10, 1.0, v35
	v_rcp_f32_e32 v0, v0
	v_rcp_f32_e32 v35, v10
	v_pk_mul_f32 v[32:33], v[14:15], v[14:15]
	v_pk_mul_f32 v[48:49], v[16:17], v[16:17]
	v_pk_mul_f32 v[0:1], v[0:1], v[18:19]
	v_pk_mul_f32 v[18:19], v[34:35], v[20:21]
	v_and_b32_e32 v21, 0xffff0000, v2
	v_pk_mul_f32 v[0:1], v[0:1], v[36:37]
	v_mul_f32_e32 v10, 0xbfb8aa3b, v21
	v_lshlrev_b32_e32 v36, 16, v3
	v_lshlrev_b32_e32 v20, 16, v2
	v_exp_f32_e32 v10, v10
	v_and_b32_e32 v37, 0xffff0000, v3
	v_mul_f32_e32 v3, 0xbfb8aa3b, v36
	v_mul_f32_e32 v2, 0xbfb8aa3b, v20
	v_exp_f32_e32 v29, v3
	v_mul_f32_e32 v3, 0xbfb8aa3b, v37
	v_pk_mul_f32 v[18:19], v[18:19], v[38:39]
	v_exp_f32_e32 v2, v2
	v_exp_f32_e32 v39, v3
	v_add_f32_e32 v10, 1.0, v10
	v_rcp_f32_e32 v3, v10
	v_add_f32_e32 v10, 1.0, v29
	v_add_f32_e32 v2, 1.0, v2
	v_rcp_f32_e32 v38, v10
	v_add_f32_e32 v10, 1.0, v39
	v_rcp_f32_e32 v2, v2
	v_rcp_f32_e32 v39, v10
	v_pk_mul_f32 v[46:47], v[6:7], v[6:7]
	v_add_f32_e32 v10, v48, v49
	v_add_f32_e32 v29, v32, v33
	v_add_f32_e32 v10, v29, v10
	v_add_f32_e32 v29, v46, v47
	v_add_f32_e32 v32, v44, v45
	v_pk_mul_f32 v[34:35], v[0:1], v[0:1]
	v_pk_mul_f32 v[50:51], v[18:19], v[18:19]
	v_pk_mul_f32 v[2:3], v[2:3], v[20:21]
	v_pk_mul_f32 v[20:21], v[38:39], v[36:37]
	v_add_f32_e32 v29, v32, v29
	v_pk_mul_f32 v[2:3], v[2:3], v[40:41]
	v_pk_mul_f32 v[20:21], v[20:21], v[42:43]
	v_add_f32_e32 v10, v29, v10
	v_add_f32_e32 v29, v50, v51
	v_add_f32_e32 v32, v34, v35
	v_pk_mul_f32 v[36:37], v[2:3], v[2:3]
	v_pk_mul_f32 v[38:39], v[20:21], v[20:21]
	v_add_f32_e32 v29, v32, v29
	v_add_f32_e32 v10, v10, v29
	v_add_f32_e32 v29, v38, v39
	v_add_f32_e32 v32, v36, v37
	v_add_f32_e32 v29, v32, v29
	v_add_f32_e32 v10, v10, v29
	ds_bpermute_b32 v29, v22, v10
	s_waitcnt lgkmcnt(0)
	v_add_f32_e32 v29, v10, v29
	ds_bpermute_b32 v32, v23, v29
	v_lshlrev_b32_e32 v10, 3, v27
	s_and_saveexec_b64 s[12:13], s[2:3]
	s_cbranch_execz .LBB0_931
	s_lshl_b32 s2, s20, 2
	v_add3_u32 v26, v24, v10, s2
	s_waitcnt lgkmcnt(0)
	v_add_f32_e32 v27, v29, v32
	ds_write_b32 v26, v27
